# gMLP unit epilogue (layer 0): the 46 serialized u/bias read-modify-write loads hoisted into one prefetch block before the MFMA section; epilogue consumes registers, waits removed
# speedup vs baseline: 1.0091x; 1.0082x over previous
; __device__ __forceinline__ unsigned cvt_pk_bf16(float lo, float hi) { unsigned r; asm volatile("v_cvt_pk_bf16_f32 %0, %1, %2" : "=v"(r) : "v"(lo), "v"(hi)); return r; }
;     __device__ __forceinline__ bf16_t* bfp(size_t off) const { return (bf16_t*)(ws + off); }
; __device__ void gmlp_unit(const Ctx& c, int tid, int l, int ch, int g, unsigned short* T) {
;     const KParams pk = c.p;
;     const int lane = tid & 63, wave = tid >> 6;
;     const int r32 = lane & 31, hi = lane >> 5, pblk = wave >> 1, cb0 = (wave & 1) * 2;
;     const float* wsr = pk->in[10] + ((size_t)(l * 8 + g) * 128 + pblk * 32 + r32) * 128 + hi * 8;
;     const bf16_t* vn = c.bfp(WS_VN) + (size_t)(ch * 128) * 1024 + g * 128;
;     bf16_t* AM0 = c.bfp(WS_AM);
;     {
;         const int q = tid >> 4, c8 = (tid & 15) * 8;
;         u32x4 v[4];
; #pragma unroll
;         for (int ps = 0; ps < 4; ++ps) v[ps] = *(const u32x4*)(vn + (size_t)(q + 32 * ps) * 1024 + c8);
; #pragma unroll
;         for (int ps = 0; ps < 4; ++ps) { unsigned short* d = T + (q + 32 * ps) * 132 + c8; *(u32x2*)d = (u32x2){v[ps].x, v[ps].y}; *(u32x2*)(d + 4) = (u32x2){v[ps].z, v[ps].w}; }
;     }
;     bf16x8 af[8];
; #pragma unroll
;     for (int ks = 0; ks < 8; ++ks) { const f32x4 a0 = *(const f32x4*)(wsr + ks * 16), a1 = *(const f32x4*)(wsr + ks * 16 + 4);
;         u32x4 aw; aw.x = cvt_pk_bf16(a0[0], a0[1]); aw.y = cvt_pk_bf16(a0[2], a0[3]); aw.z = cvt_pk_bf16(a1[0], a1[1]); aw.w = cvt_pk_bf16(a1[2], a1[3]);
;         af[ks] = *reinterpret_cast<const bf16x8*>(&aw); }
;     __syncthreads();
;     f32x16 acc0 = {}, acc1 = {};
;     const unsigned short* tb = T + (hi * 8) * 132 + cb0 * 32 + r32;
; #pragma unroll
;     for (int ks = 0; ks < 8; ++ks) {
;         bf16x8 b0, b1;
; #pragma unroll
;         for (int j = 0; j < 8; ++j) { b0[j] = (short)tb[(ks * 16 + j) * 132]; b1[j] = (short)tb[(ks * 16 + j) * 132 + 32]; }
.LBB0_464:
	s_ashr_i32 s6, s35, 3
	s_lshl_b32 s16, s6, 7
	s_ashr_i32 s17, s16, 31
	s_and_b32 s4, s10, 0x380
	s_lshl_b64 s[16:17], s[16:17], 11
	s_add_u32 s7, s8, s16
	v_lshl_add_u64 v[0:1], v[32:33], 0, s[4:5]
	v_add_u32_e32 v86, s4, v44
	s_addc_u32 s15, s9, s17
	s_lshl_b32 s4, s4, 1
	s_add_u32 s16, s7, s4
	s_addc_u32 s17, s15, 0
	v_lshlrev_b64 v[0:1], 9, v[0:1]
	v_lshl_add_u64 v[8:9], s[16:17], 0, v[34:35]
	v_lshl_add_u64 v[24:25], v[78:79], 0, v[0:1]
	v_lshl_add_u64 v[26:27], v[8:9], 0, v[36:37]
	global_load_dwordx4 v[0:3], v[24:25], off offset:16
	global_load_dwordx4 v[4:7], v[24:25], off
	v_lshl_add_u64 v[28:29], v[8:9], 0, v[38:39]
	v_lshl_add_u64 v[30:31], v[8:9], 0, v[40:41]
	v_lshl_add_u64 v[84:85], v[8:9], 0, v[42:43]
	global_load_dwordx4 v[8:11], v[26:27], off
	global_load_dwordx4 v[12:15], v[28:29], off
	global_load_dwordx4 v[16:19], v[30:31], off
	global_load_dwordx4 v[20:23], v[84:85], off
	v_add_u32_e32 v91, 0x2100, v45
	v_add_u32_e32 v92, 0x4200, v45
	v_add_u32_e32 v93, 0x6300, v45
	s_ashr_i32 s7, s6, 31
	s_lshl_b64 s[6:7], s[6:7], 18
	s_add_u32 s6, s43, s6
	s_addc_u32 s7, s56, s7
	s_add_u32 s6, s6, s4
	v_mov_b32_e32 v81, v35
	s_addc_u32 s7, s7, 0
	v_mov_b32_e32 v83, v35
	v_lshl_add_u64 v[26:27], s[6:7], 0, v[80:81]
	v_lshl_add_u64 v[84:85], v[26:27], 0, v[82:83]
	v_ashrrev_i32_e32 v87, 31, v86
	v_lshl_add_u64 v[88:89], v[84:85], 0, v[46:47]
	s_add_i32 s35, s35, s38
	s_add_i32 s10, s10, s11
	s_cmpk_lt_i32 s35, 0x240
	s_waitcnt vmcnt(0)
	ds_write2_b64 v45, v[8:9], v[10:11] offset1:1
	ds_write2_b64 v91, v[12:13], v[14:15] offset1:1
	ds_write2_b64 v92, v[16:17], v[18:19] offset1:1
	ds_write2_b64 v93, v[20:21], v[22:23] offset1:1
	v_cvt_pk_bf16_f32 v4, v4, v5
	v_cvt_pk_bf16_f32 v5, v6, v7
	v_cvt_pk_bf16_f32 v6, v0, v1
	v_cvt_pk_bf16_f32 v7, v2, v3
	global_load_dwordx4 v[0:3], v[24:25], off offset:64
	global_load_dwordx4 v[8:11], v[24:25], off offset:80
	s_waitcnt vmcnt(1)
	v_cvt_pk_bf16_f32 v92, v0, v1
	v_cvt_pk_bf16_f32 v93, v2, v3
	s_waitcnt vmcnt(0)
	v_cvt_pk_bf16_f32 v94, v8, v9
	v_cvt_pk_bf16_f32 v95, v10, v11
	global_load_dwordx4 v[0:3], v[24:25], off offset:128
	global_load_dwordx4 v[8:11], v[24:25], off offset:144
	s_waitcnt vmcnt(1)
	v_cvt_pk_bf16_f32 v96, v0, v1
	v_cvt_pk_bf16_f32 v97, v2, v3
	s_waitcnt vmcnt(0)
	v_cvt_pk_bf16_f32 v98, v8, v9
	v_cvt_pk_bf16_f32 v99, v10, v11
	global_load_dwordx4 v[0:3], v[24:25], off offset:192
	global_load_dwordx4 v[8:11], v[24:25], off offset:208
	s_waitcnt vmcnt(1)
	v_cvt_pk_bf16_f32 v100, v0, v1
	v_cvt_pk_bf16_f32 v101, v2, v3
	s_waitcnt vmcnt(0)
	v_cvt_pk_bf16_f32 v102, v8, v9
	v_cvt_pk_bf16_f32 v103, v10, v11
	global_load_dwordx4 v[0:3], v[24:25], off offset:256
	global_load_dwordx4 v[8:11], v[24:25], off offset:272
	s_waitcnt vmcnt(1)
	v_cvt_pk_bf16_f32 v104, v0, v1
	v_cvt_pk_bf16_f32 v105, v2, v3
	s_waitcnt vmcnt(0)
	v_cvt_pk_bf16_f32 v106, v8, v9
	v_cvt_pk_bf16_f32 v107, v10, v11
	global_load_dwordx4 v[0:3], v[24:25], off offset:320
	global_load_dwordx4 v[8:11], v[24:25], off offset:336
	s_waitcnt vmcnt(1)
	v_cvt_pk_bf16_f32 v108, v0, v1
	v_cvt_pk_bf16_f32 v109, v2, v3
	s_waitcnt vmcnt(0)
	v_cvt_pk_bf16_f32 v110, v8, v9
	v_cvt_pk_bf16_f32 v111, v10, v11
	global_load_dwordx4 v[0:3], v[24:25], off offset:384
	global_load_dwordx4 v[8:11], v[24:25], off offset:400
	s_waitcnt vmcnt(1)
	v_cvt_pk_bf16_f32 v112, v0, v1
	v_cvt_pk_bf16_f32 v113, v2, v3
	s_waitcnt vmcnt(0)
	v_cvt_pk_bf16_f32 v114, v8, v9
	v_cvt_pk_bf16_f32 v115, v10, v11
	global_load_dwordx4 v[0:3], v[24:25], off offset:448
	global_load_dwordx4 v[8:11], v[24:25], off offset:464
	s_waitcnt vmcnt(1)
	v_cvt_pk_bf16_f32 v116, v0, v1
	v_cvt_pk_bf16_f32 v117, v2, v3
	s_waitcnt vmcnt(0)
	v_cvt_pk_bf16_f32 v118, v8, v9
	v_cvt_pk_bf16_f32 v119, v10, v11
	s_waitcnt lgkmcnt(0)
	s_barrier
	ds_read_u16 v0, v90
	ds_read_u16 v8, v90 offset:64
	ds_read_u16 v9, v90 offset:264
	ds_read_u16 v10, v90 offset:328
	ds_read_u16 v1, v90 offset:528
	ds_read_u16 v11, v90 offset:592
	ds_read_u16 v12, v90 offset:792
	ds_read_u16 v13, v90 offset:856
	ds_read_u16 v2, v90 offset:1056
	ds_read_u16 v14, v90 offset:1120
	ds_read_u16 v15, v90 offset:1320
	ds_read_u16 v81, v90 offset:1384
	ds_read_u16 v3, v90 offset:1584
	ds_read_u16 v83, v90 offset:1648
	ds_read_u16 v16, v90 offset:1848
	ds_read_u16 v91, v90 offset:1912
	ds_read_u16 v120, v90 offset:4224
	ds_read_u16 v124, v90 offset:4288
	ds_read_u16 v125, v90 offset:4488
	ds_read_u16 v126, v90 offset:4552
	ds_read_u16 v121, v90 offset:4752
	ds_read_u16 v127, v90 offset:4816
	ds_read_u16 v128, v90 offset:5016
	ds_read_u16 v129, v90 offset:5080
	ds_read_u16 v122, v90 offset:5280
	ds_read_u16 v130, v90 offset:5344
	ds_read_u16 v131, v90 offset:5544
	ds_read_u16 v132, v90 offset:5608
	ds_read_u16 v123, v90 offset:5808
	ds_read_u16 v133, v90 offset:5872
	ds_read_u16 v134, v90 offset:6072
	ds_read_u16 v135, v90 offset:6136
	ds_read_u16 v136, v90 offset:8448
	ds_read_u16 v137, v90 offset:8512
	ds_read_u16 v138, v90 offset:8712
	ds_read_u16 v139, v90 offset:8776
	ds_read_u16 v140, v90 offset:8976
	ds_read_u16 v141, v90 offset:9040
	ds_read_u16 v142, v90 offset:9240
	ds_read_u16 v143, v90 offset:9304
	ds_read_u16 v144, v90 offset:9504
	ds_read_u16 v145, v90 offset:9568
	ds_read_u16 v146, v90 offset:9768
	ds_read_u16 v147, v90 offset:9832
	ds_read_u16 v148, v90 offset:10032
	ds_read_u16 v149, v90 offset:10096
	ds_read_u16 v150, v90 offset:10296
	ds_read_u16 v151, v90 offset:10360
	ds_read_u16 v152, v90 offset:12672
	ds_read_u16 v153, v90 offset:12736
	ds_read_u16 v154, v90 offset:12936
	ds_read_u16 v155, v90 offset:13000
	ds_read_u16 v156, v90 offset:13200
	ds_read_u16 v157, v90 offset:13264
	ds_read_u16 v158, v90 offset:13464
	ds_read_u16 v159, v90 offset:13528
	ds_read_u16 v160, v90 offset:13728
	ds_read_u16 v161, v90 offset:13792
	ds_read_u16 v162, v90 offset:13992
	ds_read_u16 v163, v90 offset:14056
	ds_read_u16 v164, v90 offset:14256
	ds_read_u16 v165, v90 offset:14320
	ds_read_u16 v166, v90 offset:14520
	ds_read_u16 v167, v90 offset:14584
	ds_read_u16 v168, v90 offset:16896
	ds_read_u16 v169, v90 offset:16960
	ds_read_u16 v170, v90 offset:17160
	ds_read_u16 v171, v90 offset:17224
	ds_read_u16 v172, v90 offset:17424
	ds_read_u16 v173, v90 offset:17488
	ds_read_u16 v174, v90 offset:17688
	ds_read_u16 v175, v90 offset:17752
	ds_read_u16 v176, v90 offset:17952
	ds_read_u16 v177, v90 offset:18016
	ds_read_u16 v178, v90 offset:18216
	ds_read_u16 v179, v90 offset:18280
	ds_read_u16 v180, v90 offset:18480
	ds_read_u16 v181, v90 offset:18544
	ds_read_u16 v182, v90 offset:18744
	ds_read_u16 v183, v90 offset:18808
	ds_read_u16 v184, v90 offset:21120
	ds_read_u16 v185, v90 offset:21184
	ds_read_u16 v186, v90 offset:21384
	ds_read_u16 v187, v90 offset:21448
	ds_read_u16 v188, v90 offset:21648
	ds_read_u16 v189, v90 offset:21712
	ds_read_u16 v190, v90 offset:21912
	ds_read_u16 v191, v90 offset:21976
	ds_read_u16 v192, v90 offset:22176
	ds_read_u16 v193, v90 offset:22240
	s_waitcnt lgkmcnt(14)
; __device__ __forceinline__ float bf2f(bf16_t b) { return __uint_as_float(((unsigned)b) << 16); }
; __device__ __forceinline__ bf16_t f2bf(float f) { return (bf16_t)(cvt_pk_bf16(f, 0.f) & 0xffffu); }
; __device__ __forceinline__ int crow(int r, int hi) { return (r & 3) + 8 * (r >> 2) + 4 * hi; }
; __device__ void gmlp_unit(const Ctx& c, int tid, int l, int ch, int g, unsigned short* T) {
;     ...
;     for (int ks = 0; ks < 8; ++ks) {
;         bf16x8 b0, b1;
; #pragma unroll
;         for (int j = 0; j < 8; ++j) { b0[j] = (short)tb[(ks * 16 + j) * 132]; b1[j] = (short)tb[(ks * 16 + j) * 132 + 32]; }
;         acc0 = __builtin_amdgcn_mfma_f32_32x32x16_bf16(af[ks], b0, acc0, 0, 0, 0);
;         acc1 = __builtin_amdgcn_mfma_f32_32x32x16_bf16(af[ks], b1, acc1, 0, 0, 0); }
; #pragma unroll
;     for (int r = 0; r < 16; ++r) { const int prow = pblk * 32 + att::crow(r, hi); const size_t t = (size_t)ch * 128 + prow;
;         const float bias = pk->in[11][(l * 8 + g) * 128 + prow];
;         bf16_t* up = AM0 + t * 1024 + g * 128 + cb0 * 32 + r32;
;         up[0] = f2bf(bf2f(up[0]) * (acc0[r] + bias)); up[32] = f2bf(bf2f(up[32]) * (acc1[r] + bias)); }
	v_perm_b32 v3, v16, v3, s14
	v_perm_b32 v2, v15, v2, s14
	v_perm_b32 v1, v12, v1, s14
	v_perm_b32 v0, v9, v0, s14
	v_perm_b32 v123, v134, v123, s14
	v_perm_b32 v122, v131, v122, s14
	v_mfma_f32_32x32x16_bf16 v[16:31], v[4:7], v[0:3], 0
	v_perm_b32 v3, v91, v83, s14
	v_perm_b32 v2, v81, v14, s14
	v_perm_b32 v1, v13, v11, s14
	v_perm_b32 v0, v10, v8, s14
	v_perm_b32 v121, v128, v121, s14
	v_perm_b32 v120, v125, v120, s14
	ds_read_u16 v194, v90 offset:22440
	ds_read_u16 v195, v90 offset:22504
	ds_read_u16 v196, v90 offset:22704
	v_mfma_f32_32x32x16_bf16 v[0:15], v[4:7], v[0:3], 0
	ds_read_u16 v81, v90 offset:22768
	ds_read_u16 v83, v90 offset:22968
	ds_read_u16 v91, v90 offset:23032
	ds_read_u16 v125, v90 offset:25344
	ds_read_u16 v128, v90 offset:25408
	ds_read_u16 v131, v90 offset:25608
	v_mfma_f32_32x32x16_bf16 v[16:31], v[92:95], v[120:123], v[16:31]
	v_perm_b32 v123, v135, v133, s14
	v_perm_b32 v122, v132, v130, s14
	v_perm_b32 v121, v129, v127, s14
	v_perm_b32 v120, v126, v124, s14
	s_nop 1
	v_mfma_f32_32x32x16_bf16 v[0:15], v[92:95], v[120:123], v[0:15]
	v_perm_b32 v95, v150, v148, s14
	v_perm_b32 v94, v146, v144, s14
	v_perm_b32 v93, v142, v140, s14
	v_perm_b32 v92, v138, v136, s14
	ds_read_u16 v120, v90 offset:25672
	ds_read_u16 v121, v90 offset:25872
	ds_read_u16 v122, v90 offset:25936
	ds_read_u16 v123, v90 offset:26136
	ds_read_u16 v124, v90 offset:26200
	ds_read_u16 v126, v90 offset:26400
	v_mfma_f32_32x32x16_bf16 v[16:31], v[96:99], v[92:95], v[16:31]
	v_perm_b32 v95, v151, v149, s14
	v_perm_b32 v94, v147, v145, s14
	v_perm_b32 v93, v143, v141, s14
	v_perm_b32 v92, v139, v137, s14
	s_nop 1
	v_mfma_f32_32x32x16_bf16 v[0:15], v[96:99], v[92:95], v[0:15]
	v_perm_b32 v95, v166, v164, s14
	v_perm_b32 v94, v162, v160, s14
	v_perm_b32 v93, v158, v156, s14
	v_perm_b32 v92, v154, v152, s14
	ds_read_u16 v96, v90 offset:26464
	ds_read_u16 v97, v90 offset:26664
	ds_read_u16 v98, v90 offset:26728
	ds_read_u16 v99, v90 offset:26928
	ds_read_u16 v127, v90 offset:26992
	ds_read_u16 v129, v90 offset:27192
	v_mfma_f32_32x32x16_bf16 v[16:31], v[100:103], v[92:95], v[16:31]
	v_perm_b32 v95, v167, v165, s14
	v_perm_b32 v94, v163, v161, s14
	v_perm_b32 v93, v159, v157, s14
	v_perm_b32 v92, v155, v153, s14
	s_nop 1
	v_mfma_f32_32x32x16_bf16 v[0:15], v[100:103], v[92:95], v[0:15]
	s_waitcnt lgkmcnt(14)
	v_perm_b32 v95, v182, v180, s14
	v_perm_b32 v94, v178, v176, s14
	v_perm_b32 v93, v174, v172, s14
	v_perm_b32 v92, v170, v168, s14
	ds_read_u16 v100, v90 offset:27256
	ds_read_u16 v101, v90 offset:29568
	ds_read_u16 v102, v90 offset:29632
	ds_read_u16 v103, v90 offset:29832
	ds_read_u16 v130, v90 offset:29896
	ds_read_u16 v132, v90 offset:30096
	v_mfma_f32_32x32x16_bf16 v[16:31], v[104:107], v[92:95], v[16:31]
	v_perm_b32 v95, v183, v181, s14
	v_perm_b32 v94, v179, v177, s14
	v_perm_b32 v93, v175, v173, s14
	v_perm_b32 v92, v171, v169, s14
	s_nop 1
	v_mfma_f32_32x32x16_bf16 v[0:15], v[104:107], v[92:95], v[0:15]
	ds_read_u16 v104, v90 offset:30160
	ds_read_u16 v105, v90 offset:30360
	ds_read_u16 v106, v90 offset:30424
	s_load_dwordx2 s[6:7], s[2:3], 0x58
	v_perm_b32 v95, v83, v196, s14
	v_perm_b32 v94, v194, v192, s14
	v_perm_b32 v93, v190, v188, s14
	v_perm_b32 v92, v186, v184, s14
	s_waitcnt lgkmcnt(0)
	v_lshl_add_u64 v[86:87], v[86:87], 2, s[6:7]
	global_load_ushort v83, v[88:89], off
	v_mfma_f32_32x32x16_bf16 v[16:31], v[108:111], v[92:95], v[16:31]
	v_perm_b32 v95, v91, v81, s14
	global_load_dword v81, v[86:87], off
	global_load_ushort v197, v[88:89], off offset:64
	v_lshl_add_u64 v[198:199], v[84:85], 0, v[48:49]
	global_load_ushort v230, v[198:199], off offset:64
	global_load_ushort v198, v[198:199], off
	global_load_dword v199, v[86:87], off offset:4
	v_lshl_add_u64 v[200:201], v[84:85], 0, v[50:51]
	global_load_ushort v231, v[200:201], off offset:64
	global_load_ushort v200, v[200:201], off
	global_load_dword v201, v[86:87], off offset:8
	v_lshl_add_u64 v[202:203], v[84:85], 0, v[52:53]
	global_load_ushort v232, v[202:203], off offset:64
	global_load_ushort v202, v[202:203], off
	global_load_dword v203, v[86:87], off offset:12
	v_lshl_add_u64 v[204:205], v[84:85], 0, v[54:55]
	global_load_ushort v233, v[204:205], off offset:64
	global_load_ushort v204, v[204:205], off
	global_load_dword v205, v[86:87], off offset:32
	v_lshl_add_u64 v[206:207], v[84:85], 0, v[56:57]
	global_load_ushort v234, v[206:207], off offset:64
	global_load_ushort v206, v[206:207], off
	global_load_dword v207, v[86:87], off offset:36
	v_lshl_add_u64 v[208:209], v[84:85], 0, v[58:59]
	global_load_ushort v235, v[208:209], off offset:64
	global_load_ushort v208, v[208:209], off
	global_load_dword v209, v[86:87], off offset:40
	v_lshl_add_u64 v[210:211], v[84:85], 0, v[60:61]
	global_load_ushort v236, v[210:211], off offset:64
	global_load_ushort v210, v[210:211], off
	global_load_dword v211, v[86:87], off offset:44
	v_lshl_add_u64 v[212:213], v[84:85], 0, v[62:63]
	global_load_ushort v237, v[212:213], off offset:64
	global_load_ushort v212, v[212:213], off
	global_load_dword v213, v[86:87], off offset:64
	v_lshl_add_u64 v[214:215], v[84:85], 0, v[64:65]
	global_load_ushort v238, v[214:215], off offset:64
	global_load_ushort v214, v[214:215], off
	global_load_dword v215, v[86:87], off offset:68
	v_lshl_add_u64 v[218:219], v[84:85], 0, v[66:67]
	global_load_ushort v239, v[218:219], off offset:64
	global_load_ushort v218, v[218:219], off
	global_load_dword v219, v[86:87], off offset:72
	v_lshl_add_u64 v[220:221], v[84:85], 0, v[68:69]
	global_load_ushort v240, v[220:221], off offset:64
	global_load_ushort v220, v[220:221], off
	global_load_dword v221, v[86:87], off offset:76
	v_lshl_add_u64 v[222:223], v[84:85], 0, v[70:71]
	global_load_ushort v241, v[222:223], off offset:64
	global_load_ushort v222, v[222:223], off
	global_load_dword v223, v[86:87], off offset:96
	v_lshl_add_u64 v[224:225], v[84:85], 0, v[72:73]
	global_load_ushort v242, v[224:225], off offset:64
	global_load_ushort v224, v[224:225], off
	global_load_dword v225, v[86:87], off offset:100
	v_lshl_add_u64 v[226:227], v[84:85], 0, v[74:75]
	global_load_ushort v243, v[226:227], off offset:64
	global_load_ushort v226, v[226:227], off
	global_load_dword v227, v[86:87], off offset:104
	v_lshl_add_u64 v[228:229], v[84:85], 0, v[76:77]
	global_load_ushort v244, v[228:229], off offset:64
	global_load_ushort v228, v[228:229], off
	global_load_dword v229, v[86:87], off offset:108
	v_perm_b32 v94, v195, v193, s14
	v_perm_b32 v93, v191, v189, s14
	v_perm_b32 v92, v187, v185, s14
	ds_read_u16 v91, v90 offset:30624
	ds_read_u16 v107, v90 offset:30688
	s_waitcnt vmcnt(47)
; __device__ void gmlp_unit(const Ctx& c, int tid, int l, int ch, int g, unsigned short* T) {
;     ...
; #pragma unroll
;     for (int ks = 0; ks < 8; ++ks) {
;         bf16x8 b0, b1;
; #pragma unroll
;         for (int j = 0; j < 8; ++j) { b0[j] = (short)tb[(ks * 16 + j) * 132]; b1[j] = (short)tb[(ks * 16 + j) * 132 + 32]; }
;         acc0 = __builtin_amdgcn_mfma_f32_32x32x16_bf16(af[ks], b0, acc0, 0, 0, 0);
;         acc1 = __builtin_amdgcn_mfma_f32_32x32x16_bf16(af[ks], b1, acc1, 0, 0, 0); }
	v_lshlrev_b32_e32 v83, 16, v83
	v_mfma_f32_32x32x16_bf16 v[0:15], v[108:111], v[92:95], v[0:15]
	v_perm_b32 v95, v129, v99, s14
	v_perm_b32 v94, v97, v126, s14
	v_perm_b32 v93, v123, v121, s14
	v_perm_b32 v92, v131, v125, s14
	ds_read_u16 v97, v90 offset:30888
	ds_read_u16 v99, v90 offset:31152
	ds_read_u16 v108, v90 offset:31416
	v_mfma_f32_32x32x16_bf16 v[16:31], v[112:115], v[92:95], v[16:31]
	v_perm_b32 v95, v100, v127, s14
	v_perm_b32 v94, v98, v96, s14
	v_perm_b32 v93, v124, v122, s14
	v_perm_b32 v92, v120, v128, s14
	ds_read_u16 v98, v90 offset:30952
	ds_read_u16 v100, v90 offset:31216
	ds_read_u16 v109, v90 offset:31480
	v_mfma_f32_32x32x16_bf16 v[0:15], v[112:115], v[92:95], v[0:15]
	s_waitcnt lgkmcnt(3)
	v_perm_b32 v95, v108, v99, s14
	v_perm_b32 v94, v97, v91, s14
	v_perm_b32 v93, v105, v132, s14
	v_perm_b32 v92, v103, v101, s14
	v_lshl_add_u64 v[96:97], v[84:85], 0, v[48:49]
	s_nop 0
	v_mfma_f32_32x32x16_bf16 v[16:31], v[116:119], v[92:95], v[16:31]
	s_waitcnt lgkmcnt(0)
	v_perm_b32 v95, v109, v100, s14
	v_perm_b32 v94, v98, v107, s14
	v_perm_b32 v93, v106, v104, s14
	v_perm_b32 v92, v130, v102, s14
	s_nop 1
	v_mfma_f32_32x32x16_bf16 v[0:15], v[116:119], v[92:95], v[0:15]
	s_waitcnt vmcnt(0)
; __device__ __forceinline__ float bf2f(bf16_t b) { return __uint_as_float(((unsigned)b) << 16); }
; __device__ __forceinline__ bf16_t f2bf(float f) { return (bf16_t)(cvt_pk_bf16(f, 0.f) & 0xffffu); }
; __device__ __forceinline__ int crow(int r, int hi) { return (r & 3) + 8 * (r >> 2) + 4 * hi; }
; __device__ void gmlp_unit(const Ctx& c, int tid, int l, int ch, int g, unsigned short* T) {
;     ...
; #pragma unroll
;     for (int r = 0; r < 16; ++r) { const int prow = pblk * 32 + att::crow(r, hi); const size_t t = (size_t)ch * 128 + prow;
;         const float bias = pk->in[11][(l * 8 + g) * 128 + prow];
;         bf16_t* up = AM0 + t * 1024 + g * 128 + cb0 * 32 + r32;
;         up[0] = f2bf(bf2f(up[0]) * (acc0[r] + bias)); up[32] = f2bf(bf2f(up[32]) * (acc1[r] + bias)); }
;     __syncthreads();
	s_nop 2
	v_add_f32_e32 v16, v16, v81
	v_mul_f32_e32 v16, v16, v83
	v_cvt_pk_bf16_f32 v16, v16, v35
	v_mov_b32_e32 v83, v197
	s_nop 0
	global_store_short v[88:89], v16, off
	s_nop 2
	v_add_f32_e32 v0, v0, v81
	v_lshlrev_b32_e32 v16, 16, v83
	v_mul_f32_e32 v0, v0, v16
	v_cvt_pk_bf16_f32 v0, v0, v35
	v_mov_b32_e32 v16, v198
	v_mov_b32_e32 v81, v199
	v_add_f32_e32 v1, v1, v81
	global_store_short v[88:89], v0, off offset:64
	v_lshlrev_b32_e32 v0, 16, v16
	v_add_f32_e32 v16, v17, v81
	v_mul_f32_e32 v0, v16, v0
	v_cvt_pk_bf16_f32 v0, v0, v35
	v_mov_b32_e32 v83, v230
	v_lshl_add_u64 v[16:17], v[84:85], 0, v[50:51]
	global_store_short v[96:97], v0, off
	v_lshlrev_b32_e32 v0, 16, v83
	v_mul_f32_e32 v0, v1, v0
	v_cvt_pk_bf16_f32 v0, v0, v35
	v_mov_b32_e32 v1, v200
	v_mov_b32_e32 v81, v201
	v_add_f32_e32 v2, v2, v81
	global_store_short v[96:97], v0, off offset:64
	v_lshlrev_b32_e32 v0, 16, v1
	v_add_f32_e32 v1, v18, v81
	v_mul_f32_e32 v0, v1, v0
	v_cvt_pk_bf16_f32 v18, v0, v35
	v_mov_b32_e32 v83, v231
	v_lshl_add_u64 v[0:1], v[84:85], 0, v[52:53]
	global_store_short v[16:17], v18, off
	v_lshlrev_b32_e32 v18, 16, v83
	v_mul_f32_e32 v2, v2, v18
	v_cvt_pk_bf16_f32 v2, v2, v35
	v_mov_b32_e32 v18, v202
	v_mov_b32_e32 v81, v203
	v_add_f32_e32 v3, v3, v81
	global_store_short v[16:17], v2, off offset:64
	v_lshlrev_b32_e32 v2, 16, v18
	v_add_f32_e32 v16, v19, v81
	v_mul_f32_e32 v2, v16, v2
	v_cvt_pk_bf16_f32 v2, v2, v35
	v_mov_b32_e32 v18, v232
	v_lshl_add_u64 v[16:17], v[84:85], 0, v[54:55]
	global_store_short v[0:1], v2, off
	v_lshlrev_b32_e32 v2, 16, v18
	v_mul_f32_e32 v2, v3, v2
	v_cvt_pk_bf16_f32 v2, v2, v35
	v_mov_b32_e32 v3, v204
	v_mov_b32_e32 v18, v205
	v_add_f32_e32 v4, v4, v18
	global_store_short v[0:1], v2, off offset:64
	v_lshlrev_b32_e32 v0, 16, v3
	v_add_f32_e32 v1, v20, v18
	v_mul_f32_e32 v0, v1, v0
	v_cvt_pk_bf16_f32 v2, v0, v35
	v_mov_b32_e32 v3, v233
	v_lshl_add_u64 v[0:1], v[84:85], 0, v[56:57]
	global_store_short v[16:17], v2, off
	v_lshlrev_b32_e32 v2, 16, v3
	v_mul_f32_e32 v2, v4, v2
	v_cvt_pk_bf16_f32 v2, v2, v35
	v_mov_b32_e32 v3, v206
	v_mov_b32_e32 v4, v207
	s_nop 0
	global_store_short v[16:17], v2, off offset:64
	v_lshlrev_b32_e32 v2, 16, v3
	v_add_f32_e32 v3, v21, v4
	v_mul_f32_e32 v2, v3, v2
	v_cvt_pk_bf16_f32 v16, v2, v35
	v_mov_b32_e32 v17, v234
	v_add_f32_e32 v4, v5, v4
	v_lshl_add_u64 v[2:3], v[84:85], 0, v[58:59]
	global_store_short v[0:1], v16, off
	v_lshlrev_b32_e32 v5, 16, v17
	v_mul_f32_e32 v4, v4, v5
	v_cvt_pk_bf16_f32 v4, v4, v35
	v_mov_b32_e32 v5, v208
	v_mov_b32_e32 v16, v209
	v_add_f32_e32 v6, v6, v16
	global_store_short v[0:1], v4, off offset:64
	v_lshlrev_b32_e32 v0, 16, v5
	v_add_f32_e32 v1, v22, v16
	v_mul_f32_e32 v0, v1, v0
	v_cvt_pk_bf16_f32 v4, v0, v35
	v_mov_b32_e32 v5, v235
	v_lshl_add_u64 v[0:1], v[84:85], 0, v[60:61]
	global_store_short v[2:3], v4, off
	v_lshlrev_b32_e32 v4, 16, v5
	v_mul_f32_e32 v4, v6, v4
	v_cvt_pk_bf16_f32 v4, v4, v35
	v_mov_b32_e32 v5, v210
	v_mov_b32_e32 v6, v211
	s_nop 0
	global_store_short v[2:3], v4, off offset:64
	v_lshlrev_b32_e32 v2, 16, v5
	v_add_f32_e32 v3, v23, v6
	v_mul_f32_e32 v2, v3, v2
	v_cvt_pk_bf16_f32 v4, v2, v35
	v_mov_b32_e32 v5, v236
	v_add_f32_e32 v6, v7, v6
	global_store_short v[0:1], v4, off
	v_lshl_add_u64 v[2:3], v[84:85], 0, v[62:63]
	v_lshlrev_b32_e32 v4, 16, v5
	v_mul_f32_e32 v4, v6, v4
	v_cvt_pk_bf16_f32 v4, v4, v35
	v_mov_b32_e32 v5, v212
	v_mov_b32_e32 v6, v213
	s_nop 0
	global_store_short v[0:1], v4, off offset:64
	v_lshlrev_b32_e32 v0, 16, v5
	v_add_f32_e32 v1, v24, v6
	v_mul_f32_e32 v0, v1, v0
	v_cvt_pk_bf16_f32 v4, v0, v35
	v_mov_b32_e32 v5, v237
	v_add_f32_e32 v6, v8, v6
	global_store_short v[2:3], v4, off
	v_lshl_add_u64 v[0:1], v[84:85], 0, v[64:65]
	v_lshlrev_b32_e32 v4, 16, v5
	v_mul_f32_e32 v4, v6, v4
	v_cvt_pk_bf16_f32 v4, v4, v35
	v_mov_b32_e32 v5, v214
	v_mov_b32_e32 v6, v215
	s_nop 0
	global_store_short v[2:3], v4, off offset:64
	v_lshlrev_b32_e32 v2, 16, v5
	v_add_f32_e32 v3, v25, v6
	v_mul_f32_e32 v2, v3, v2
	v_cvt_pk_bf16_f32 v4, v2, v35
	v_mov_b32_e32 v5, v238
	v_add_f32_e32 v6, v9, v6
	global_store_short v[0:1], v4, off
	v_lshl_add_u64 v[2:3], v[84:85], 0, v[66:67]
	v_lshlrev_b32_e32 v4, 16, v5
	v_mul_f32_e32 v4, v6, v4
	v_cvt_pk_bf16_f32 v4, v4, v35
	v_mov_b32_e32 v5, v218
	v_mov_b32_e32 v6, v219
	s_nop 0
	global_store_short v[0:1], v4, off offset:64
	v_lshlrev_b32_e32 v0, 16, v5
	v_add_f32_e32 v1, v26, v6
	v_mul_f32_e32 v0, v1, v0
	v_cvt_pk_bf16_f32 v4, v0, v35
	v_mov_b32_e32 v5, v239
	v_add_f32_e32 v6, v10, v6
	global_store_short v[2:3], v4, off
	v_lshl_add_u64 v[0:1], v[84:85], 0, v[68:69]
	v_lshlrev_b32_e32 v4, 16, v5
	v_mul_f32_e32 v4, v6, v4
	v_cvt_pk_bf16_f32 v4, v4, v35
	v_mov_b32_e32 v5, v220
	v_mov_b32_e32 v6, v221
	s_nop 0
	global_store_short v[2:3], v4, off offset:64
	v_lshlrev_b32_e32 v2, 16, v5
	v_add_f32_e32 v3, v27, v6
	v_mul_f32_e32 v2, v3, v2
	v_cvt_pk_bf16_f32 v4, v2, v35
	v_mov_b32_e32 v5, v240
	v_add_f32_e32 v6, v11, v6
	global_store_short v[0:1], v4, off
	v_lshl_add_u64 v[2:3], v[84:85], 0, v[70:71]
	v_lshlrev_b32_e32 v4, 16, v5
	v_mul_f32_e32 v4, v6, v4
	v_cvt_pk_bf16_f32 v4, v4, v35
	v_mov_b32_e32 v5, v222
	v_mov_b32_e32 v6, v223
	s_nop 0
	global_store_short v[0:1], v4, off offset:64
	v_lshlrev_b32_e32 v0, 16, v5
	v_add_f32_e32 v1, v28, v6
	v_mul_f32_e32 v0, v1, v0
	v_cvt_pk_bf16_f32 v4, v0, v35
	v_mov_b32_e32 v5, v241
	v_add_f32_e32 v6, v12, v6
	global_store_short v[2:3], v4, off
	v_lshl_add_u64 v[0:1], v[84:85], 0, v[72:73]
	v_lshlrev_b32_e32 v4, 16, v5
	v_mul_f32_e32 v4, v6, v4
	v_cvt_pk_bf16_f32 v4, v4, v35
	v_mov_b32_e32 v5, v224
	v_mov_b32_e32 v6, v225
	s_nop 0
	global_store_short v[2:3], v4, off offset:64
	v_lshlrev_b32_e32 v2, 16, v5
	v_add_f32_e32 v3, v29, v6
	v_mul_f32_e32 v2, v3, v2
	v_cvt_pk_bf16_f32 v4, v2, v35
	v_mov_b32_e32 v5, v242
	v_add_f32_e32 v6, v13, v6
	global_store_short v[0:1], v4, off
	v_lshl_add_u64 v[2:3], v[84:85], 0, v[74:75]
	v_lshlrev_b32_e32 v4, 16, v5
	v_mul_f32_e32 v4, v6, v4
	v_cvt_pk_bf16_f32 v4, v4, v35
	v_mov_b32_e32 v5, v226
	v_mov_b32_e32 v6, v227
	s_nop 0
	global_store_short v[0:1], v4, off offset:64
	v_lshlrev_b32_e32 v0, 16, v5
	v_add_f32_e32 v1, v30, v6
	v_mul_f32_e32 v0, v1, v0
	v_cvt_pk_bf16_f32 v4, v0, v35
	v_mov_b32_e32 v5, v243
	v_add_f32_e32 v6, v14, v6
	global_store_short v[2:3], v4, off
	v_lshl_add_u64 v[0:1], v[84:85], 0, v[76:77]
	v_lshlrev_b32_e32 v4, 16, v5
	v_mul_f32_e32 v4, v6, v4
	v_cvt_pk_bf16_f32 v4, v4, v35
	v_mov_b32_e32 v5, v228
	v_mov_b32_e32 v6, v229
	s_nop 0
	global_store_short v[2:3], v4, off offset:64
	v_lshlrev_b32_e32 v2, 16, v5
	v_add_f32_e32 v3, v31, v6
	v_mul_f32_e32 v2, v3, v2
	v_cvt_pk_bf16_f32 v2, v2, v35
	v_mov_b32_e32 v3, v244
	v_add_f32_e32 v4, v15, v6
	global_store_short v[0:1], v2, off
	v_lshlrev_b32_e32 v2, 16, v3
	v_mul_f32_e32 v2, v4, v2
	v_cvt_pk_bf16_f32 v2, v2, v35
	global_store_short v[0:1], v2, off offset:64
	s_barrier
	s_cbranch_scc1 .LBB0_464
